# P5: the softmax wave of each row group runs at raised issue priority
# speedup vs baseline: 1.0099x; 1.0099x over previous
.Lp5n_loop:
	s_and_b32 s51, s98, 1
	s_and_b32 s101, s98, 6
	s_lshl_b32 s61, s100, 3
	s_add_i32 s61, s61, s101
	s_lshl_b32 s62, s61, 4
	s_lshl_b32 s101, s94, 8
	s_add_i32 s62, s62, s101
	v_or_b32_e32 v130, s62, v120
	s_lshl_b32 s50, s51, 4
	v_add_u32_e32 v16, s50, v130
	v_ashrrev_i32_e32 v17, 31, v16
	v_lshlrev_b64 v[16:17], 12, v[16:17]
	v_mov_b32_e32 v135, 0
	v_lshl_add_u64 v[118:119], v[96:97], 0, v[16:17]
	v_mov_b32_e32 v16, 0
	v_mov_b32_e32 v17, v135
	v_mov_b32_e32 v18, v135
	v_mov_b32_e32 v19, v135
	s_lshl_b32 s0, s99, 10
	s_mov_b32 s1, 0
	s_lshl_b32 s101, s99, 13
	v_add_u32_e32 v84, s101, v129
	v_lshl_add_u64 v[236:237], v[118:119], 0, s[0:1]
	global_load_dwordx4 v[148:151], v[236:237], off offset:16
	global_load_dwordx4 v[152:155], v[236:237], off
	global_load_dwordx4 v[156:159], v[236:237], off offset:144
	global_load_dwordx4 v[160:163], v[236:237], off offset:128
	global_load_dwordx4 v[164:167], v[236:237], off offset:272
	global_load_dwordx4 v[168:171], v[236:237], off offset:256
	global_load_dwordx4 v[172:175], v[236:237], off offset:400
	global_load_dwordx4 v[176:179], v[236:237], off offset:384
	global_load_dwordx4 v[196:199], v[236:237], off offset:528
	global_load_dwordx4 v[200:203], v[236:237], off offset:512
	global_load_dwordx4 v[204:207], v[236:237], off offset:656
	global_load_dwordx4 v[208:211], v[236:237], off offset:640
	global_load_dwordx4 v[212:215], v[236:237], off offset:768
	global_load_dwordx4 v[216:219], v[236:237], off offset:784
	global_load_dwordx4 v[220:223], v[236:237], off offset:912
	global_load_dwordx4 v[224:227], v[236:237], off offset:896
	v_add_u32_e32 v238, s50, v130
	v_ashrrev_i32_e32 v239, 31, v238
	v_lshlrev_b64 v[238:239], 11, v[238:239]
	v_lshl_add_u64 v[238:239], s[78:79], 0, v[238:239]
	v_lshl_add_u64 v[238:239], v[238:239], 0, v[240:241]
	s_waitcnt vmcnt(0)
	v_mov_b64_e32 v[80:81], v[148:149]
	v_mov_b64_e32 v[82:83], v[150:151]
	v_mov_b64_e32 v[136:137], v[152:153]
	v_mov_b64_e32 v[138:139], v[154:155]
	v_mov_b64_e32 v[68:69], v[156:157]
	v_mov_b64_e32 v[70:71], v[158:159]
	v_mov_b64_e32 v[72:73], v[160:161]
	v_mov_b64_e32 v[74:75], v[162:163]
	v_mov_b64_e32 v[60:61], v[164:165]
	v_mov_b64_e32 v[62:63], v[166:167]
	v_mov_b64_e32 v[64:65], v[168:169]
	v_mov_b64_e32 v[66:67], v[170:171]
	v_mov_b64_e32 v[52:53], v[172:173]
	v_mov_b64_e32 v[54:55], v[174:175]
	v_mov_b64_e32 v[56:57], v[176:177]
	v_mov_b64_e32 v[58:59], v[178:179]
	v_mov_b64_e32 v[44:45], v[196:197]
	v_mov_b64_e32 v[46:47], v[198:199]
	v_mov_b64_e32 v[48:49], v[200:201]
	v_mov_b64_e32 v[50:51], v[202:203]
	v_mov_b64_e32 v[36:37], v[204:205]
	v_mov_b64_e32 v[38:39], v[206:207]
	v_mov_b64_e32 v[40:41], v[208:209]
	v_mov_b64_e32 v[42:43], v[210:211]
	v_mov_b64_e32 v[32:33], v[212:213]
	v_mov_b64_e32 v[34:35], v[214:215]
	v_mov_b64_e32 v[28:29], v[216:217]
	v_mov_b64_e32 v[30:31], v[218:219]
	v_mov_b64_e32 v[20:21], v[220:221]
	v_mov_b64_e32 v[22:23], v[222:223]
	v_mov_b64_e32 v[24:25], v[224:225]
	v_mov_b64_e32 v[26:27], v[226:227]
	v_cvt_pk_bf16_f32 v78, v80, v81
	v_fmac_f32_e32 v135, v136, v136
	v_fmac_f32_e32 v135, v137, v137
	v_fmac_f32_e32 v135, v138, v138
	v_cvt_pk_bf16_f32 v76, v136, v137
	v_cvt_pk_bf16_f32 v77, v138, v139
	v_fmac_f32_e32 v135, v139, v139
	v_lshlrev_b32_e32 v140, 16, v76
	v_and_b32_e32 v141, 0xffff0000, v76
	v_lshlrev_b32_e32 v142, 16, v77
	v_and_b32_e32 v143, 0xffff0000, v77
	v_lshlrev_b32_e32 v144, 16, v78
	v_and_b32_e32 v145, 0xffff0000, v78
	v_sub_f32_e32 v140, v136, v140
	v_sub_f32_e32 v141, v137, v141
	v_sub_f32_e32 v142, v138, v142
	v_sub_f32_e32 v143, v139, v143
	v_fmac_f32_e32 v135, v80, v80
	v_sub_f32_e32 v144, v80, v144
	v_sub_f32_e32 v145, v81, v145
	v_fmac_f32_e32 v135, v81, v81
	v_cvt_pk_bf16_f32 v80, v140, v141
	v_cvt_pk_bf16_f32 v81, v142, v143
	ds_read_b128 v[136:139], v84
	ds_read_b128 v[140:143], v84 offset:32768
	v_cvt_pk_bf16_f32 v79, v82, v83
	v_fmac_f32_e32 v135, v82, v82
	s_waitcnt lgkmcnt(1)
	v_mfma_f32_16x16x32_bf16 v[16:19], v[76:79], v[136:139], v[16:19]
	v_lshlrev_b32_e32 v146, 16, v79
	v_and_b32_e32 v147, 0xffff0000, v79
	v_sub_f32_e32 v146, v82, v146
	v_sub_f32_e32 v147, v83, v147
	v_fmac_f32_e32 v135, v83, v83
	v_cvt_pk_bf16_f32 v82, v144, v145
	v_cvt_pk_bf16_f32 v83, v146, v147
	v_fmac_f32_e32 v135, v72, v72
	v_mfma_f32_16x16x32_bf16 v[16:19], v[80:83], v[136:139], v[16:19]
	v_fmac_f32_e32 v135, v73, v73
	v_fmac_f32_e32 v135, v74, v74
	v_fmac_f32_e32 v135, v75, v75
	s_waitcnt lgkmcnt(0)
	v_mfma_f32_16x16x32_bf16 v[16:19], v[76:79], v[140:143], v[16:19]
	v_cvt_pk_bf16_f32 v76, v72, v73
	v_cvt_pk_bf16_f32 v77, v74, v75
	v_cvt_pk_bf16_f32 v78, v68, v69
	v_fmac_f32_e32 v135, v68, v68
	v_lshlrev_b32_e32 v80, 16, v76
	v_and_b32_e32 v81, 0xffff0000, v76
	v_lshlrev_b32_e32 v82, 16, v77
	v_and_b32_e32 v83, 0xffff0000, v77
	v_lshlrev_b32_e32 v136, 16, v78
	v_and_b32_e32 v137, 0xffff0000, v78
	v_sub_f32_e32 v80, v72, v80
	v_sub_f32_e32 v81, v73, v81
	v_sub_f32_e32 v82, v74, v82
	v_sub_f32_e32 v83, v75, v83
	v_sub_f32_e32 v136, v68, v136
	v_sub_f32_e32 v137, v69, v137
	v_fmac_f32_e32 v135, v69, v69
	v_cvt_pk_bf16_f32 v68, v80, v81
	v_cvt_pk_bf16_f32 v69, v82, v83
	ds_read_b128 v[72:75], v84 offset:1024
	ds_read_b128 v[80:83], v84 offset:33792
	v_cvt_pk_bf16_f32 v79, v70, v71
	v_fmac_f32_e32 v135, v70, v70
	s_waitcnt lgkmcnt(1)
	v_mfma_f32_16x16x32_bf16 v[16:19], v[76:79], v[72:75], v[16:19]
	v_lshlrev_b32_e32 v138, 16, v79
	v_and_b32_e32 v139, 0xffff0000, v79
	v_fmac_f32_e32 v135, v71, v71
	v_sub_f32_e32 v138, v70, v138
	v_sub_f32_e32 v139, v71, v139
	v_cvt_pk_bf16_f32 v70, v136, v137
	v_cvt_pk_bf16_f32 v71, v138, v139
	v_fmac_f32_e32 v135, v64, v64
	v_mfma_f32_16x16x32_bf16 v[16:19], v[68:71], v[72:75], v[16:19]
	v_fmac_f32_e32 v135, v65, v65
	v_fmac_f32_e32 v135, v66, v66
	v_cvt_pk_bf16_f32 v68, v64, v65
	v_cvt_pk_bf16_f32 v69, v66, v67
	v_fmac_f32_e32 v135, v67, v67
	v_lshlrev_b32_e32 v72, 16, v68
	v_and_b32_e32 v73, 0xffff0000, v68
	v_lshlrev_b32_e32 v74, 16, v69
	v_and_b32_e32 v75, 0xffff0000, v69
	s_waitcnt lgkmcnt(0)
	v_mfma_f32_16x16x32_bf16 v[16:19], v[76:79], v[80:83], v[16:19]
	v_cvt_pk_bf16_f32 v70, v60, v61
	v_sub_f32_e32 v72, v64, v72
	v_lshlrev_b32_e32 v76, 16, v70
	v_and_b32_e32 v77, 0xffff0000, v70
	v_sub_f32_e32 v73, v65, v73
	v_sub_f32_e32 v74, v66, v74
	v_sub_f32_e32 v75, v67, v75
	v_fmac_f32_e32 v135, v60, v60
	v_sub_f32_e32 v76, v60, v76
	v_sub_f32_e32 v77, v61, v77
	v_fmac_f32_e32 v135, v61, v61
	v_cvt_pk_bf16_f32 v60, v72, v73
	v_cvt_pk_bf16_f32 v61, v74, v75
	ds_read_b128 v[64:67], v84 offset:2048
	ds_read_b128 v[72:75], v84 offset:34816
	v_cvt_pk_bf16_f32 v71, v62, v63
	v_fmac_f32_e32 v135, v62, v62
	s_waitcnt lgkmcnt(1)
	v_mfma_f32_16x16x32_bf16 v[16:19], v[68:71], v[64:67], v[16:19]
	v_lshlrev_b32_e32 v78, 16, v71
	v_and_b32_e32 v79, 0xffff0000, v71
	v_fmac_f32_e32 v135, v63, v63
	v_sub_f32_e32 v78, v62, v78
	v_sub_f32_e32 v79, v63, v79
	v_cvt_pk_bf16_f32 v62, v76, v77
	v_cvt_pk_bf16_f32 v63, v78, v79
	v_fmac_f32_e32 v135, v56, v56
	v_mfma_f32_16x16x32_bf16 v[16:19], v[60:63], v[64:67], v[16:19]
	v_fmac_f32_e32 v135, v57, v57
	v_fmac_f32_e32 v135, v58, v58
	v_cvt_pk_bf16_f32 v60, v56, v57
	v_cvt_pk_bf16_f32 v61, v58, v59
	v_fmac_f32_e32 v135, v59, v59
	v_lshlrev_b32_e32 v64, 16, v60
	v_and_b32_e32 v65, 0xffff0000, v60
	v_lshlrev_b32_e32 v66, 16, v61
	v_and_b32_e32 v67, 0xffff0000, v61
	s_waitcnt lgkmcnt(0)
	v_mfma_f32_16x16x32_bf16 v[16:19], v[68:71], v[72:75], v[16:19]
	v_cvt_pk_bf16_f32 v62, v52, v53
	v_sub_f32_e32 v64, v56, v64
	v_lshlrev_b32_e32 v68, 16, v62
	v_and_b32_e32 v69, 0xffff0000, v62
	v_sub_f32_e32 v65, v57, v65
	v_sub_f32_e32 v66, v58, v66
	v_sub_f32_e32 v67, v59, v67
	v_fmac_f32_e32 v135, v52, v52
	v_sub_f32_e32 v68, v52, v68
	v_sub_f32_e32 v69, v53, v69
	v_fmac_f32_e32 v135, v53, v53
	v_cvt_pk_bf16_f32 v52, v64, v65
	v_cvt_pk_bf16_f32 v53, v66, v67
	ds_read_b128 v[56:59], v84 offset:3072
	ds_read_b128 v[64:67], v84 offset:35840
	v_cvt_pk_bf16_f32 v63, v54, v55
	v_fmac_f32_e32 v135, v54, v54
	s_waitcnt lgkmcnt(1)
	v_mfma_f32_16x16x32_bf16 v[16:19], v[60:63], v[56:59], v[16:19]
	v_lshlrev_b32_e32 v70, 16, v63
	v_and_b32_e32 v71, 0xffff0000, v63
	v_fmac_f32_e32 v135, v55, v55
	v_sub_f32_e32 v70, v54, v70
	v_sub_f32_e32 v71, v55, v71
	v_cvt_pk_bf16_f32 v54, v68, v69
	v_cvt_pk_bf16_f32 v55, v70, v71
	v_fmac_f32_e32 v135, v48, v48
	v_mfma_f32_16x16x32_bf16 v[16:19], v[52:55], v[56:59], v[16:19]
	v_fmac_f32_e32 v135, v49, v49
	v_fmac_f32_e32 v135, v50, v50
	v_cvt_pk_bf16_f32 v52, v48, v49
	v_cvt_pk_bf16_f32 v53, v50, v51
	v_fmac_f32_e32 v135, v51, v51
	v_lshlrev_b32_e32 v56, 16, v52
	v_and_b32_e32 v57, 0xffff0000, v52
	v_lshlrev_b32_e32 v58, 16, v53
	v_and_b32_e32 v59, 0xffff0000, v53
	s_waitcnt lgkmcnt(0)
	v_mfma_f32_16x16x32_bf16 v[16:19], v[60:63], v[64:67], v[16:19]
	v_cvt_pk_bf16_f32 v54, v44, v45
	v_sub_f32_e32 v56, v48, v56
	v_lshlrev_b32_e32 v60, 16, v54
	v_and_b32_e32 v61, 0xffff0000, v54
	v_sub_f32_e32 v57, v49, v57
	v_sub_f32_e32 v58, v50, v58
	v_sub_f32_e32 v59, v51, v59
	v_fmac_f32_e32 v135, v44, v44
	v_sub_f32_e32 v60, v44, v60
	v_sub_f32_e32 v61, v45, v61
	v_fmac_f32_e32 v135, v45, v45
	v_cvt_pk_bf16_f32 v44, v56, v57
	v_cvt_pk_bf16_f32 v45, v58, v59
	ds_read_b128 v[48:51], v84 offset:4096
	ds_read_b128 v[56:59], v84 offset:36864
	v_cvt_pk_bf16_f32 v55, v46, v47
	v_fmac_f32_e32 v135, v46, v46
	s_waitcnt lgkmcnt(1)
	v_mfma_f32_16x16x32_bf16 v[16:19], v[52:55], v[48:51], v[16:19]
	v_lshlrev_b32_e32 v62, 16, v55
	v_and_b32_e32 v63, 0xffff0000, v55
	v_fmac_f32_e32 v135, v47, v47
	v_sub_f32_e32 v62, v46, v62
	v_sub_f32_e32 v63, v47, v63
	v_cvt_pk_bf16_f32 v46, v60, v61
	v_cvt_pk_bf16_f32 v47, v62, v63
	v_fmac_f32_e32 v135, v40, v40
	v_mfma_f32_16x16x32_bf16 v[16:19], v[44:47], v[48:51], v[16:19]
	v_fmac_f32_e32 v135, v41, v41
	v_fmac_f32_e32 v135, v42, v42
	v_cvt_pk_bf16_f32 v44, v40, v41
	v_cvt_pk_bf16_f32 v45, v42, v43
	v_fmac_f32_e32 v135, v43, v43
	v_lshlrev_b32_e32 v48, 16, v44
	v_and_b32_e32 v49, 0xffff0000, v44
	v_lshlrev_b32_e32 v50, 16, v45
	v_and_b32_e32 v51, 0xffff0000, v45
	s_waitcnt lgkmcnt(0)
	v_mfma_f32_16x16x32_bf16 v[16:19], v[52:55], v[56:59], v[16:19]
	v_cvt_pk_bf16_f32 v46, v36, v37
	v_sub_f32_e32 v48, v40, v48
	v_lshlrev_b32_e32 v52, 16, v46
	v_and_b32_e32 v53, 0xffff0000, v46
	v_sub_f32_e32 v49, v41, v49
	v_sub_f32_e32 v50, v42, v50
	v_sub_f32_e32 v51, v43, v51
	v_fmac_f32_e32 v135, v36, v36
	v_sub_f32_e32 v52, v36, v52
	v_sub_f32_e32 v53, v37, v53
	v_fmac_f32_e32 v135, v37, v37
	v_cvt_pk_bf16_f32 v36, v48, v49
	v_cvt_pk_bf16_f32 v37, v50, v51
	ds_read_b128 v[40:43], v84 offset:5120
	ds_read_b128 v[48:51], v84 offset:37888
	v_cvt_pk_bf16_f32 v47, v38, v39
	v_fmac_f32_e32 v135, v38, v38
	s_waitcnt lgkmcnt(1)
	v_mfma_f32_16x16x32_bf16 v[16:19], v[44:47], v[40:43], v[16:19]
	v_lshlrev_b32_e32 v54, 16, v47
	v_and_b32_e32 v55, 0xffff0000, v47
	v_sub_f32_e32 v54, v38, v54
	v_sub_f32_e32 v55, v39, v55
	v_fmac_f32_e32 v135, v39, v39
	v_cvt_pk_bf16_f32 v38, v52, v53
	v_cvt_pk_bf16_f32 v39, v54, v55
	v_fmac_f32_e32 v135, v32, v32
	v_mfma_f32_16x16x32_bf16 v[16:19], v[36:39], v[40:43], v[16:19]
	v_mov_b32_e32 v36, v28
	v_mov_b32_e32 v37, v35
	v_pk_mul_f32 v[42:43], v[30:31], v[30:31]
	v_fmac_f32_e32 v135, v33, v33
	v_pk_mul_f32 v[40:41], v[36:37], v[36:37]
	v_cvt_pk_bf16_f32 v36, v32, v33
	v_fmac_f32_e32 v135, v34, v34
	v_lshlrev_b32_e32 v43, 16, v36
	s_waitcnt lgkmcnt(0)
	v_mfma_f32_16x16x32_bf16 v[16:19], v[44:47], v[48:51], v[16:19]
	v_mul_f32_e64 v44, v28, v28
	v_mul_f32_e64 v45, v29, v29
	v_sub_f32_e32 v43, v32, v43
	v_add_f32_e32 v32, v41, v135
	v_cvt_pk_bf16_f32 v37, v34, v35
	v_cvt_pk_bf16_f32 v39, v30, v31
	v_and_b32_e32 v44, 0xffff0000, v36
	v_lshlrev_b32_e32 v46, 16, v37
	v_and_b32_e32 v47, 0xffff0000, v37
	v_and_b32_e32 v51, 0xffff0000, v39
	v_add_f32_e32 v32, v40, v32
	v_cvt_pk_bf16_f32 v38, v28, v29
	v_lshlrev_b32_e32 v50, 16, v39
	v_lshlrev_b32_e32 v48, 16, v38
	v_sub_f32_e32 v44, v33, v44
	v_sub_f32_e32 v46, v34, v46
	v_sub_f32_e32 v35, v35, v47
	v_sub_f32_e32 v47, v31, v51
	v_add_f32_e32 v32, v45, v32
	v_sub_f32_e32 v28, v28, v48
	v_sub_f32_e32 v30, v30, v50
	v_add_f32_e32 v48, v42, v32
	v_cvt_pk_bf16_f32 v32, v43, v44
	v_cvt_pk_bf16_f32 v33, v46, v35
	v_cvt_pk_bf16_f32 v35, v30, v47
	ds_read_b128 v[40:43], v84 offset:6144
	ds_read_b128 v[44:47], v84 offset:38912
	s_waitcnt lgkmcnt(1)
	v_mfma_f32_16x16x32_bf16 v[16:19], v[36:39], v[40:43], v[16:19]
	v_and_b32_e32 v49, 0xffff0000, v38
	v_sub_f32_e32 v29, v29, v49
	v_cvt_pk_bf16_f32 v34, v28, v29
	v_mov_b32_e32 v30, v24
	v_mfma_f32_16x16x32_bf16 v[16:19], v[32:35], v[40:43], v[16:19]
	v_mul_f32_e64 v32, v30, v30
	v_mul_f32_e64 v33, v31, v31
	v_pk_mul_f32 v[34:35], v[26:27], v[26:27]
	v_mov_b32_e32 v28, v20
	v_mov_b32_e32 v29, v27
	s_waitcnt lgkmcnt(0)
	v_mfma_f32_16x16x32_bf16 v[16:19], v[36:39], v[44:47], v[16:19]
	v_add_f32_e32 v33, v33, v48
	v_pk_mul_f32 v[38:39], v[28:29], v[28:29]
	v_cvt_pk_bf16_f32 v28, v24, v25
	v_cvt_pk_bf16_f32 v30, v20, v21
	v_pk_mul_f32 v[36:37], v[24:25], v[24:25]
	v_lshlrev_b32_e32 v35, 16, v28
	v_lshlrev_b32_e32 v44, 16, v30
	v_pk_mul_f32 v[42:43], v[20:21], v[20:21]
	v_sub_f32_e32 v24, v24, v35
	v_sub_f32_e32 v35, v20, v44
	v_add_f32_e32 v20, v32, v33
	v_add_f32_e32 v20, v37, v20
	v_add_f32_e32 v20, v34, v20
	v_pk_mul_f32 v[40:41], v[22:23], v[22:23]
	v_add_f32_e32 v20, v39, v20
	v_cvt_pk_bf16_f32 v29, v26, v27
	v_and_b32_e32 v36, 0xffff0000, v28
	v_lshlrev_b32_e32 v41, 16, v29
	v_and_b32_e32 v42, 0xffff0000, v29
	v_add_f32_e32 v20, v38, v20
	v_cvt_pk_bf16_f32 v31, v22, v23
	v_and_b32_e32 v45, 0xffff0000, v30
	v_lshlrev_b32_e32 v46, 16, v31
	v_sub_f32_e32 v25, v25, v36
	v_sub_f32_e32 v26, v26, v41
	v_sub_f32_e32 v27, v27, v42
	v_add_f32_e32 v20, v43, v20
	v_sub_f32_e32 v36, v21, v45
	v_sub_f32_e32 v41, v22, v46
	v_add_f32_e32 v135, v40, v20
	v_cvt_pk_bf16_f32 v20, v24, v25
	v_cvt_pk_bf16_f32 v21, v26, v27
	v_cvt_pk_bf16_f32 v22, v35, v36
	ds_read_b128 v[24:27], v84 offset:7168
	ds_read_b128 v[32:35], v84 offset:39936
	s_waitcnt lgkmcnt(1)
	v_mfma_f32_16x16x32_bf16 v[16:19], v[28:31], v[24:27], v[16:19]
	v_and_b32_e32 v47, 0xffff0000, v31
	v_sub_f32_e32 v42, v23, v47
	v_fmac_f32_e32 v135, v23, v23
	v_cvt_pk_bf16_f32 v23, v41, v42
	v_add_u32_e32 v84, 0x2000, v84
	v_mfma_f32_16x16x32_bf16 v[16:19], v[20:23], v[24:27], v[16:19]
	s_waitcnt lgkmcnt(0)
	v_mfma_f32_16x16x32_bf16 v[16:19], v[28:31], v[32:35], v[16:19]
	s_nop 7
	s_nop 7
	ds_write_b128 v231, v[16:19]
	ds_write_b32 v232, v135
	s_waitcnt lgkmcnt(0)
	s_barrier
	ds_read_b128 v[16:19], v233
	ds_read_b128 v[20:23], v233 offset:1280
	ds_read_b128 v[24:27], v233 offset:2560
	ds_read_b128 v[28:31], v233 offset:3840
	ds_read_b32 v135, v234
	ds_read_b32 v32, v234 offset:1280
	ds_read_b32 v33, v234 offset:2560
	ds_read_b32 v34, v234 offset:3840
	s_waitcnt lgkmcnt(0)
	v_pk_add_f32 v[16:17], v[16:17], v[20:21]
	v_pk_add_f32 v[18:19], v[18:19], v[22:23]
	v_pk_add_f32 v[16:17], v[16:17], v[24:25]
	v_pk_add_f32 v[18:19], v[18:19], v[26:27]
	v_pk_add_f32 v[16:17], v[16:17], v[28:29]
	v_pk_add_f32 v[18:19], v[18:19], v[30:31]
	v_add_f32_e32 v135, v135, v32
	v_add_f32_e32 v135, v135, v33
	v_add_f32_e32 v135, v135, v34
	v_and_b32_e32 v24, 64, v133
	v_xor_b32_e32 v20, 16, v133
	v_add_u32_e32 v21, 64, v24
	v_cmp_lt_i32_e32 vcc, v20, v21
	v_xor_b32_e32 v22, 32, v133
	s_mov_b32 s0, 0x800000
	v_cndmask_b32_e32 v20, v133, v20, vcc
	v_lshlrev_b32_e32 v20, 2, v20
	ds_bpermute_b32 v20, v20, v135
	v_cmp_lt_i32_e32 vcc, v22, v21
	v_or_b32_e32 v25, v24, v122
	v_lshlrev_b32_e32 v25, 2, v25
	v_cndmask_b32_e32 v22, v133, v22, vcc
	s_waitcnt lgkmcnt(0)
	v_add_f32_e32 v20, v135, v20
	v_lshlrev_b32_e32 v22, 2, v22
	ds_bpermute_b32 v22, v22, v20
	v_xor_b32_e32 v23, 1, v133
	v_or_b32_e32 v28, v24, v123
	s_add_i32 s84, s62, s50
	s_mov_b32 s85, -4
	s_waitcnt lgkmcnt(0)
	v_add_f32_e32 v20, v20, v22
	v_fmamk_f32 v20, v20, 0x3a800000, v132
	v_mul_f32_e32 v22, 0x4b800000, v20
	v_cmp_gt_f32_e32 vcc, s0, v20
	s_or_b32 s0, s51, s61
	s_lshl_b32 s0, s0, 4
	v_cndmask_b32_e32 v20, v20, v22, vcc
	v_rsq_f32_e32 v20, v20
	v_xor_b32_e32 v22, 2, v133
	s_add_i32 s0, s0, s33
	s_and_b32 s0, s0, 0xff0
	v_mul_f32_e32 v26, 0x45800000, v20
	v_cndmask_b32_e32 v64, v20, v26, vcc
	s_cmp_lg_u32 s99, 0
	s_cbranch_scc1 .Lp5n_nosm
	s_setprio 2
	ds_bpermute_b32 v20, v25, v64
	v_cmp_lt_i32_e32 vcc, v23, v21
	v_xor_b32_e32 v25, 4, v133
	v_or_b32_e32 v30, s0, v122
	v_cndmask_b32_e32 v23, v133, v23, vcc
	v_lshlrev_b32_e32 v26, 2, v23
	s_waitcnt lgkmcnt(0)
	v_fma_f32 v16, v16, v20, v99
	ds_bpermute_b32 v20, v26, v16
	v_cmp_lt_i32_e32 vcc, v22, v21
	v_xor_b32_e32 v23, 8, v133
	v_lshlrev_b32_e32 v84, 2, v30
	v_cndmask_b32_e32 v22, v133, v22, vcc
	s_waitcnt lgkmcnt(0)
	v_max_f32_e32 v20, v20, v20
	v_lshlrev_b32_e32 v27, 2, v22
	v_max_f32_e32 v20, v16, v20
	ds_bpermute_b32 v22, v27, v20
	v_cmp_lt_i32_e32 vcc, v25, v21
	s_waitcnt lgkmcnt(0)
	v_max_f32_e32 v22, v22, v22
	v_cndmask_b32_e32 v25, v133, v25, vcc
	v_lshlrev_b32_e32 v29, 2, v25
	v_max_f32_e32 v20, v20, v22
	ds_bpermute_b32 v22, v29, v20
	v_lshlrev_b32_e32 v25, 2, v28
	ds_bpermute_b32 v25, v25, v64
	v_cmp_lt_i32_e32 vcc, v23, v21
	s_waitcnt lgkmcnt(0)
	v_fma_f32 v17, v17, v25, v99
	v_cndmask_b32_e32 v21, v133, v23, vcc
	v_lshlrev_b32_e32 v28, 2, v21
	v_max_f32_e32 v21, v22, v22
	v_max_f32_e32 v20, v20, v21
	ds_bpermute_b32 v22, v28, v20
	ds_bpermute_b32 v21, v26, v17
	s_waitcnt lgkmcnt(1)
	v_max_f32_e32 v22, v22, v22
	s_waitcnt lgkmcnt(0)
	v_max_f32_e32 v21, v21, v21
	v_max_f32_e32 v20, v20, v22
	v_sub_f32_e32 v16, v16, v20
	v_max_f32_e32 v20, v17, v21
	ds_bpermute_b32 v21, v27, v20
	v_mul_f32_e32 v22, 0x3fb8aa3b, v16
	v_fma_f32 v23, v16, s91, -v22
	v_rndne_f32_e32 v25, v22
	v_fmac_f32_e32 v23, 0x32a5705f, v16
	s_waitcnt lgkmcnt(0)
	v_max_f32_e32 v21, v21, v21
	v_max_f32_e32 v20, v20, v21
	ds_bpermute_b32 v21, v29, v20
	v_sub_f32_e32 v22, v22, v25
	v_add_f32_e32 v22, v22, v23
	v_exp_f32_e32 v22, v22
	v_cvt_i32_f32_e32 v23, v25
	s_waitcnt lgkmcnt(0)
	v_max_f32_e32 v21, v21, v21
	v_max_f32_e32 v20, v20, v21
	ds_bpermute_b32 v21, v28, v20
	v_ldexp_f32 v22, v22, v23
	v_cmp_ngt_f32_e32 vcc, s92, v16
	s_waitcnt lgkmcnt(0)
	v_max_f32_e32 v21, v21, v21
	v_max_f32_e32 v20, v20, v21
	v_sub_f32_e32 v17, v17, v20
	v_mul_f32_e32 v20, 0x3fb8aa3b, v17
	v_fma_f32 v21, v17, s91, -v20
	v_rndne_f32_e32 v23, v20
	v_fmac_f32_e32 v21, 0x32a5705f, v17
	v_sub_f32_e32 v20, v20, v23
	v_add_f32_e32 v20, v20, v21
	v_exp_f32_e32 v21, v20
	v_cvt_i32_f32_e32 v23, v23
	v_cndmask_b32_e32 v22, 0, v22, vcc
	v_cmp_nlt_f32_e32 vcc, s93, v16
	v_ldexp_f32 v21, v21, v23
	s_nop 0
	v_cndmask_b32_e32 v16, v134, v22, vcc
	v_cmp_ngt_f32_e32 vcc, s92, v17
	ds_bpermute_b32 v20, v26, v16
	s_nop 0
	v_cndmask_b32_e32 v21, 0, v21, vcc
	v_cmp_nlt_f32_e32 vcc, s93, v17
	s_nop 1
	v_cndmask_b32_e32 v17, v134, v21, vcc
	ds_bpermute_b32 v21, v26, v17
	s_waitcnt lgkmcnt(0)
	v_pk_add_f32 v[20:21], v[16:17], v[20:21]
	ds_bpermute_b32 v22, v27, v20
	ds_bpermute_b32 v23, v27, v21
	s_waitcnt lgkmcnt(0)
	v_pk_add_f32 v[20:21], v[20:21], v[22:23]
	v_or_b32_e32 v22, v24, v124
	v_lshlrev_b32_e32 v22, 2, v22
	ds_bpermute_b32 v25, v22, v64
	ds_bpermute_b32 v22, v29, v20
	ds_bpermute_b32 v23, v29, v21
	v_or_b32_e32 v24, v24, v125
	v_lshlrev_b32_e32 v24, 2, v24
	s_waitcnt lgkmcnt(2)
	v_fma_f32 v18, v18, v25, v99
	ds_bpermute_b32 v25, v26, v18
	s_waitcnt lgkmcnt(1)
	v_pk_add_f32 v[20:21], v[20:21], v[22:23]
	ds_bpermute_b32 v22, v28, v20
	ds_bpermute_b32 v23, v28, v21
	ds_bpermute_b32 v24, v24, v64
	s_waitcnt lgkmcnt(3)
	v_max_f32_e32 v25, v25, v25
	v_max_f32_e32 v25, v18, v25
	ds_bpermute_b32 v31, v27, v25
	s_waitcnt lgkmcnt(2)
	v_pk_add_f32 v[20:21], v[20:21], v[22:23]
	s_waitcnt lgkmcnt(1)
	v_fma_f32 v19, v19, v24, v99
	v_div_scale_f32 v32, s[0:1], v21, v21, v17
	s_waitcnt lgkmcnt(0)
	v_max_f32_e32 v22, v31, v31
	v_max_f32_e32 v25, v25, v22
	v_rcp_f32_e32 v33, v32
	ds_bpermute_b32 v31, v29, v25
	ds_bpermute_b32 v24, v26, v19
	v_lshl_add_u64 v[22:23], v[116:117], 0, v[84:85]
	v_fma_f32 v30, -v32, v33, 1.0
	v_fmac_f32_e32 v33, v30, v33
	s_waitcnt lgkmcnt(1)
	v_max_f32_e32 v30, v31, v31
	v_max_f32_e32 v25, v25, v30
	ds_bpermute_b32 v30, v28, v25
	s_waitcnt lgkmcnt(1)
	v_max_f32_e32 v24, v24, v24
	v_max_f32_e32 v24, v19, v24
	v_div_scale_f32 v31, vcc, v17, v21, v17
	s_waitcnt lgkmcnt(0)
	v_max_f32_e32 v30, v30, v30
	v_max_f32_e32 v25, v25, v30
	v_sub_f32_e32 v18, v18, v25
	ds_bpermute_b32 v25, v27, v24
	v_mul_f32_e32 v30, 0x3fb8aa3b, v18
	v_fma_f32 v35, v18, s91, -v30
	v_rndne_f32_e32 v36, v30
	v_fmac_f32_e32 v35, 0x32a5705f, v18
	s_waitcnt lgkmcnt(0)
	v_max_f32_e32 v25, v25, v25
	v_max_f32_e32 v24, v24, v25
	ds_bpermute_b32 v25, v29, v24
	v_sub_f32_e32 v30, v30, v36
	v_add_f32_e32 v30, v30, v35
	v_exp_f32_e32 v30, v30
	v_cvt_i32_f32_e32 v35, v36
	s_waitcnt lgkmcnt(0)
	v_max_f32_e32 v25, v25, v25
	v_max_f32_e32 v24, v24, v25
	ds_bpermute_b32 v25, v28, v24
	v_ldexp_f32 v30, v30, v35
	v_cmp_ngt_f32_e64 s[0:1], s92, v18
	v_mul_f32_e32 v34, v31, v33
	v_fma_f32 v36, -v32, v34, v31
	s_waitcnt lgkmcnt(0)
	v_max_f32_e32 v25, v25, v25
	v_max_f32_e32 v24, v24, v25
	v_sub_f32_e32 v19, v19, v24
	v_mul_f32_e32 v24, 0x3fb8aa3b, v19
	v_fma_f32 v25, v19, s91, -v24
	v_rndne_f32_e32 v35, v24
	v_fmac_f32_e32 v25, 0x32a5705f, v19
	v_sub_f32_e32 v24, v24, v35
	v_add_f32_e32 v24, v24, v25
	v_exp_f32_e32 v25, v24
	v_cvt_i32_f32_e32 v35, v35
	v_cndmask_b32_e64 v30, 0, v30, s[0:1]
	v_cmp_nlt_f32_e64 s[0:1], s93, v18
	v_fmac_f32_e32 v34, v36, v33
	v_ldexp_f32 v25, v25, v35
	v_cndmask_b32_e64 v18, v134, v30, s[0:1]
	v_cmp_ngt_f32_e64 s[0:1], s92, v19
	ds_bpermute_b32 v24, v26, v18
	s_nop 0
	v_cndmask_b32_e64 v25, 0, v25, s[0:1]
	v_cmp_nlt_f32_e64 s[0:1], s93, v19
	s_nop 1
	v_cndmask_b32_e64 v19, v134, v25, s[0:1]
	ds_bpermute_b32 v25, v26, v19
	v_fma_f32 v26, -v32, v34, v31
	v_div_fmas_f32 v30, v26, v33, v34
	v_div_fixup_f32 v17, v30, v21, v17
	v_div_scale_f32 v21, s[0:1], v20, v20, v16
	s_waitcnt lgkmcnt(0)
	v_pk_add_f32 v[24:25], v[18:19], v[24:25]
	ds_bpermute_b32 v26, v27, v24
	ds_bpermute_b32 v27, v27, v25
	v_rcp_f32_e32 v30, v21
	s_waitcnt lgkmcnt(0)
	v_pk_add_f32 v[24:25], v[24:25], v[26:27]
	ds_bpermute_b32 v26, v29, v24
	ds_bpermute_b32 v27, v29, v25
	v_fma_f32 v29, -v21, v30, 1.0
	v_fmac_f32_e32 v30, v29, v30
	v_div_scale_f32 v29, vcc, v16, v20, v16
	s_waitcnt lgkmcnt(0)
	v_pk_add_f32 v[24:25], v[24:25], v[26:27]
	ds_bpermute_b32 v26, v28, v24
	ds_bpermute_b32 v27, v28, v25
	v_mul_f32_e32 v28, v29, v30
	v_fma_f32 v31, -v21, v28, v29
	v_fmac_f32_e32 v28, v31, v30
	v_fma_f32 v21, -v21, v28, v29
	s_waitcnt lgkmcnt(0)
	v_pk_add_f32 v[24:25], v[24:25], v[26:27]
	v_div_fmas_f32 v21, v21, v30, v28
	v_div_scale_f32 v26, s[0:1], v25, v25, v19
	v_rcp_f32_e32 v27, v26
	v_div_fixup_f32 v16, v21, v20, v16
	v_fma_f32 v20, -v26, v27, 1.0
	v_fmac_f32_e32 v27, v20, v27
	v_div_scale_f32 v20, vcc, v19, v25, v19
	v_mul_f32_e32 v21, v20, v27
	v_fma_f32 v28, -v26, v21, v20
	v_fmac_f32_e32 v21, v28, v27
	v_fma_f32 v20, -v26, v21, v20
	v_div_scale_f32 v26, s[0:1], v24, v24, v18
	v_rcp_f32_e32 v28, v26
	v_div_fmas_f32 v20, v20, v27, v21
	v_div_fixup_f32 v19, v20, v25, v19
	v_fma_f32 v20, -v26, v28, 1.0
	v_fmac_f32_e32 v28, v20, v28
	v_div_scale_f32 v20, vcc, v18, v24, v18
	v_mul_f32_e32 v21, v20, v28
	v_fma_f32 v25, -v26, v21, v20
	v_fmac_f32_e32 v21, v25, v28
	v_fma_f32 v20, -v26, v21, v20
	v_div_fmas_f32 v20, v20, v28, v21
	v_div_fixup_f32 v18, v20, v24, v18
	global_store_dwordx4 v[22:23], v[16:19], off
	s_nop 1
	v_lshlrev_b32_e32 v16, 2, v133
	v_and_b32_e32 v65, 0x100, v16
	s_setprio 0
